# attention K/V global prefetch: wave-uniform SGPR base + 32-bit lane offset, pointer stepping on the SALU
# baseline (speedup 1.0000x reference)
.LBB0_2403:
	s_or_b64 exec, exec, s[24:25]
	v_sub_f32_e32 v136, 0, v118
	v_sub_f32_e32 v137, 0, v118
	v_sub_f32_e32 v138, 0, v118
	v_sub_f32_e32 v139, 0, v118
	v_sub_f32_e32 v140, 0, v118
	v_sub_f32_e32 v141, 0, v118
	v_sub_f32_e32 v142, 0, v118
	v_sub_f32_e32 v143, 0, v118
	v_sub_f32_e32 v144, 0, v118
	v_sub_f32_e32 v145, 0, v118
	v_sub_f32_e32 v146, 0, v118
	v_sub_f32_e32 v147, 0, v118
	v_sub_f32_e32 v148, 0, v118
	v_sub_f32_e32 v149, 0, v118
	v_sub_f32_e32 v150, 0, v118
	v_sub_f32_e32 v151, 0, v118
	s_waitcnt vmcnt(1)
	ds_write_b128 v46, v[32:35] offset:22528
	s_and_saveexec_b64 s[24:25], s[6:7]
	ds_write_b128 v45, v[64:67] offset:22528
	s_or_b64 exec, exec, s[24:25]
	s_xor_b64 s[24:25], s[26:27], -1
	s_mov_b64 s[26:27], 0x1800000
	s_sub_i32 s1, -3, s0
	v_and_b32_e32 v32, 7, v102
	v_lshl_add_u64 v[104:105], v[42:43], 0, s[26:27]
	s_add_u32 s26, s28, s10
	v_lshlrev_b32_e32 v32, 4, v32
	v_mov_b32_e32 v33, v193
	s_addc_u32 s27, s29, s11
	v_lshl_add_u64 v[32:33], v[40:41], 0, v[32:33]
	v_lshl_add_u64 v[32:33], s[26:27], 0, v[32:33]
	s_mov_b64 s[26:27], 0x1800080
	v_lshl_add_u64 v[106:107], v[32:33], 0, s[26:27]
	s_add_u32 s26, s28, s39
	s_addc_u32 s27, s29, s37
	v_lshl_add_u64 v[32:33], v[102:103], 4, s[26:27]
	v_ashrrev_i32_e32 v101, 31, v100
	v_mul_u32_u24_e32 v117, 0x90, v44
	v_lshl_add_u64 v[108:109], v[32:33], 0, s[70:71]
	s_mov_b32 s13, 1
	v_readfirstlane_b32 s44, v108
	v_readfirstlane_b32 s45, v109
	v_readfirstlane_b32 s46, v106
	v_readfirstlane_b32 s47, v107
	s_nop 1
	v_subrev_u32_e32 v188, s44, v108
	v_subrev_u32_e32 v190, s46, v106
	v_add_u32_e32 v189, 0x2000, v188
	s_nop 2
	s_waitcnt vmcnt(0)
	ds_write_b128 v47, v[36:39] offset:35840
	s_waitcnt lgkmcnt(0)
	s_barrier
	global_load_dwordx4 v[92:95], v188, s[44:45]
	s_and_saveexec_b64 s[26:27], s[6:7]
	s_cbranch_execz .LBB0_2407
.LBB0_2406:
	global_load_dwordx4 v[64:67], v189, s[44:45]
.LBB0_2407:
	s_or_b64 exec, exec, s[26:27]
	global_load_dwordx4 v[96:99], v190, s[46:47]
	s_add_i32 s26, s13, -1
	s_and_b32 s28, s13, 1
	v_cmp_le_i32_e32 vcc, s26, v114
	s_and_saveexec_b64 s[26:27], vcc
	s_cbranch_execz .LBB0_2409
	s_mul_i32 s29, s28, 0x5800
	s_add_i32 s29, s29, 0
	v_add3_u32 v119, s29, v116, v192
	ds_read_b128 v[32:35], v119 offset:6656
	ds_read_b128 v[36:39], v119
	ds_read_b128 v[120:123], v119 offset:32
	ds_read_b128 v[124:127], v119 offset:6688
	s_waitcnt lgkmcnt(2)
	v_mfma_f32_32x32x16_bf16 v[48:63], v[36:39], v[88:91], v[136:151]
	v_mfma_f32_32x32x16_bf16 v[32:47], v[32:35], v[88:91], v[136:151]
	s_waitcnt lgkmcnt(1)
	v_mfma_f32_32x32x16_bf16 v[48:63], v[120:123], v[84:87], v[48:63]
	s_waitcnt lgkmcnt(0)
	v_mfma_f32_32x32x16_bf16 v[32:47], v[124:127], v[84:87], v[32:47]
	ds_read_b128 v[120:123], v119 offset:64
	ds_read_b128 v[124:127], v119 offset:6720
	s_waitcnt lgkmcnt(1)
	v_mfma_f32_32x32x16_bf16 v[48:63], v[120:123], v[80:83], v[48:63]
	s_waitcnt lgkmcnt(0)
	v_mfma_f32_32x32x16_bf16 v[32:47], v[124:127], v[80:83], v[32:47]
	ds_read_b128 v[120:123], v119 offset:96
	ds_read_b128 v[124:127], v119 offset:6752
	s_waitcnt lgkmcnt(1)
	v_mfma_f32_32x32x16_bf16 v[48:63], v[120:123], v[76:79], v[48:63]
	s_waitcnt lgkmcnt(0)
	v_mfma_f32_32x32x16_bf16 v[32:47], v[124:127], v[76:79], v[32:47]
	ds_read_b128 v[120:123], v119 offset:128
	ds_read_b128 v[124:127], v119 offset:6784
	s_waitcnt lgkmcnt(1)
	v_mfma_f32_32x32x16_bf16 v[48:63], v[120:123], v[72:75], v[48:63]
	s_waitcnt lgkmcnt(0)
	v_mfma_f32_32x32x16_bf16 v[32:47], v[124:127], v[72:75], v[32:47]
	ds_read_b128 v[120:123], v119 offset:160
	ds_read_b128 v[124:127], v119 offset:6816
	s_waitcnt lgkmcnt(1)
	v_mfma_f32_32x32x16_bf16 v[48:63], v[120:123], v[68:71], v[48:63]
	s_waitcnt lgkmcnt(0)
	v_mfma_f32_32x32x16_bf16 v[32:47], v[124:127], v[68:71], v[32:47]
	v_add3_u32 v168, s29, v117, v192
	ds_read_b128 v[152:155], v168 offset:13312
	ds_read_b128 v[156:159], v168 offset:17920
	ds_read_b128 v[160:163], v168 offset:13344
	ds_read_b128 v[164:167], v168 offset:17952
	ds_read_b128 v[128:131], v168 offset:13376
	ds_read_b128 v[132:135], v168 offset:17984
	ds_read_b128 v[172:175], v168 offset:13408
	ds_read_b128 v[176:179], v168 offset:18016
	s_nop 1
	v_max_f32_e32 v119, v48, v49
	v_max3_f32 v119, v119, v50, v51
	v_max3_f32 v119, v119, v52, v53
	v_max3_f32 v119, v119, v54, v55
	v_max3_f32 v119, v119, v56, v57
	v_max3_f32 v119, v119, v58, v59
	v_max3_f32 v119, v119, v60, v61
	v_max3_f32 v119, v119, v62, v63
	v_max3_f32 v119, v119, v32, v33
	v_max3_f32 v119, v119, v34, v35
	v_max3_f32 v119, v119, v36, v37
	v_max3_f32 v119, v119, v38, v39
	v_max3_f32 v119, v119, v40, v41
	v_max3_f32 v119, v119, v42, v43
	v_max3_f32 v119, v119, v44, v45
	v_max3_f32 v119, v119, v46, v47
	v_cmp_lt_f32_e32 vcc, 0x41000000, v119
	s_cbranch_vccnz .Lattn_rare

.Lattn_blk_end:
.LBB0_2409:
	s_or_b64 exec, exec, s[26:27]
	s_xor_b32 s26, s28, 1
	s_mulk_i32 s26, 0x5800
	s_add_i32 s28, s26, 0
	v_add_u32_e32 v32, s28, v112
	s_waitcnt vmcnt(1)
	ds_write_b128 v32, v[92:95]
	s_and_saveexec_b64 s[26:27], s[6:7]
	v_add_u32_e32 v32, s28, v111
	ds_write_b128 v32, v[64:67]
	s_or_b64 exec, exec, s[26:27]
	v_add_u32_e32 v32, s28, v113
	s_add_i32 s28, s13, 1
	s_add_i32 s26, s1, s28
	s_add_u32 s46, s46, 0x80
	s_addc_u32 s47, s47, 0
	s_add_u32 s44, s44, 0x3000
	s_addc_u32 s45, s45, 0
	s_cmp_eq_u32 s26, 1
	s_waitcnt vmcnt(0)
	ds_write_b128 v32, v[96:99] offset:13312
	s_waitcnt lgkmcnt(0)
	s_barrier
	s_cbranch_scc1 .LBB0_2413
	s_mov_b32 s13, s28
	global_load_dwordx4 v[92:95], v188, s[44:45]
	s_and_saveexec_b64 s[26:27], s[6:7]
	s_cbranch_execnz .LBB0_2406
	s_branch .LBB0_2407
